# thin GEMMs (sample rows of P2/P7/P10): all fragment loads of a batch issued before the first MFMA (the compiler had serialised them through two registers); on top of v13
# baseline (speedup 1.0000x reference)
; __device__ __forceinline__ void thin_gemm_ln(const bf16* A, const bf16* Bt, int K, const float* base, float s, const float* g, const float* b, float* outf, bf16* outb, ...
;     ...
;         for (int s0 = 0; s0 < steps; s0 += 4) {
;             bf16x8 fa[4][2], fb[4][4];
; #pragma unroll
;             for (int q = 0; q < 4; ++q) { const int st = (s0 + q < steps) ? s0 + q : steps - 1;
;                 fa[q][0] = *(const bf16x8*)(ap + 32 * st); fa[q][1] = *(const bf16x8*)(ap + (size_t)16 * K + 32 * st);
; #pragma unroll
;                 for (int j = 0; j < 4; ++j) fb[q][j] = *(const bf16x8*)(bp + (size_t)(16 * j) * K + 32 * st); }
; #pragma unroll
;             for (int q = 0; q < 4; ++q) if (s0 + q < steps) {
; #pragma unroll
;                 for (int j = 0; j < 4; ++j) { acc[0][j] = __builtin_amdgcn_mfma_f32_16x16x32_bf16(fa[q][0], fb[q][j], acc[0][j], 0, 0, 0); acc[1][j] = __builtin_amdgcn_mfma_f32_16x16x32_bf16(fa[q][1], fb[q][j], acc[1][j], 0, 0, 0); } }
;         }
.LBB0_237:
	v_lshl_add_u64 v[38:39], s[54:55], 0, v[34:35]
	v_add_co_u32_e32 v76, vcc, 0xaa00000, v38
	v_lshl_add_u64 v[40:41], s[54:55], 0, v[36:37]
	s_nop 0
	v_addc_co_u32_e32 v77, vcc, 0, v39, vcc
	v_add_co_u32_e32 v78, vcc, 0xaa16000, v38
	s_mov_b64 s[0:1], vcc
	v_add_co_u32_e32 v80, vcc, 0xd00000, v40
	global_load_dwordx4 v[44:47], v[76:77], off
	s_nop 0
	v_addc_co_u32_e32 v81, vcc, 0, v41, vcc
	v_add_co_u32_e32 v82, vcc, 0xd16000, v40
	global_load_dwordx4 v[48:51], v[80:81], off
	global_load_dwordx4 v[52:55], v[76:77], off offset:64
	v_addc_co_u32_e32 v83, vcc, 0, v41, vcc
	v_add_co_u32_e32 v84, vcc, 0xd2c000, v40
	global_load_dwordx4 v[56:59], v[80:81], off offset:64
	global_load_dwordx4 v[60:63], v[82:83], off
	v_addc_co_u32_e32 v85, vcc, 0, v41, vcc
	v_addc_co_u32_e64 v79, vcc, 0, v39, s[0:1]
	global_load_dwordx4 v[64:67], v[84:85], off
	global_load_dwordx4 v[72:75], v[78:79], off
	v_add_co_u32_e32 v86, vcc, 0xd42000, v40
	global_load_dwordx4 v[68:71], v[84:85], off offset:64
	s_nop 0
	v_addc_co_u32_e32 v87, vcc, 0, v41, vcc
	s_cmp_gt_u32 s5, 10
	global_load_dwordx4 v[88:91], v[86:87], off
	global_load_dwordx4 v[92:95], v[78:79], off offset:128
	global_load_dwordx4 v[96:99], v[82:83], off offset:64
	global_load_dwordx4 v[100:103], v[78:79], off offset:64
	global_load_dwordx4 v[104:107], v[86:87], off offset:64
	global_load_dwordx4 v[108:111], v[84:85], off offset:128
	global_load_dwordx4 v[112:115], v[76:77], off offset:128
	global_load_dwordx4 v[116:119], v[80:81], off offset:128
	global_load_dwordx4 v[120:123], v[82:83], off offset:128
	global_load_dwordx4 v[124:127], v[86:87], off offset:128
	s_waitcnt vmcnt(16)
	v_mfma_f32_16x16x32_bf16 v[2:5], v[44:47], v[48:51], v[2:5]
	s_waitcnt vmcnt(11)
	v_mfma_f32_16x16x32_bf16 v[14:17], v[72:75], v[48:51], v[14:17]
	v_mfma_f32_16x16x32_bf16 v[30:33], v[44:47], v[60:63], v[30:33]
	v_mfma_f32_16x16x32_bf16 v[26:29], v[44:47], v[64:67], v[26:29]
	v_mfma_f32_16x16x32_bf16 v[18:21], v[72:75], v[60:63], v[18:21]
	s_waitcnt vmcnt(9)
	v_mfma_f32_16x16x32_bf16 v[22:25], v[44:47], v[88:91], v[22:25]
	v_mfma_f32_16x16x32_bf16 v[10:13], v[72:75], v[88:91], v[10:13]
	s_waitcnt vmcnt(7)
	v_mfma_f32_16x16x32_bf16 v[30:33], v[52:55], v[96:99], v[30:33]
	s_waitcnt vmcnt(6)
	v_mfma_f32_16x16x32_bf16 v[18:21], v[100:103], v[96:99], v[18:21]
	v_mfma_f32_16x16x32_bf16 v[2:5], v[52:55], v[56:59], v[2:5]
	v_mfma_f32_16x16x32_bf16 v[14:17], v[100:103], v[56:59], v[14:17]
	v_mfma_f32_16x16x32_bf16 v[26:29], v[52:55], v[68:71], v[26:29]
	s_waitcnt vmcnt(5)
	v_mfma_f32_16x16x32_bf16 v[22:25], v[52:55], v[104:107], v[22:25]
	v_mfma_f32_16x16x32_bf16 v[10:13], v[100:103], v[104:107], v[10:13]
	v_mfma_f32_16x16x32_bf16 v[6:9], v[72:75], v[64:67], v[6:9]
	v_mfma_f32_16x16x32_bf16 v[6:9], v[100:103], v[68:71], v[6:9]
	s_waitcnt vmcnt(2)
	v_mfma_f32_16x16x32_bf16 v[2:5], v[112:115], v[116:119], v[2:5]
	v_mfma_f32_16x16x32_bf16 v[14:17], v[92:95], v[116:119], v[14:17]
	s_waitcnt vmcnt(1)
	v_mfma_f32_16x16x32_bf16 v[30:33], v[112:115], v[120:123], v[30:33]
	v_mfma_f32_16x16x32_bf16 v[26:29], v[112:115], v[108:111], v[26:29]
	v_mfma_f32_16x16x32_bf16 v[18:21], v[92:95], v[120:123], v[18:21]
	v_mfma_f32_16x16x32_bf16 v[6:9], v[92:95], v[108:111], v[6:9]
	s_waitcnt vmcnt(0)
	v_mfma_f32_16x16x32_bf16 v[22:25], v[112:115], v[124:127], v[22:25]
	v_mfma_f32_16x16x32_bf16 v[10:13], v[92:95], v[124:127], v[10:13]
	s_cbranch_scc1 .LBB0_239
	v_add_co_u32_e32 v60, vcc, 0xd42000, v40
	s_nop 1
	v_addc_co_u32_e32 v61, vcc, 0, v41, vcc
	v_add_co_u32_e32 v56, vcc, 0xd2c000, v40
	s_nop 1
	v_addc_co_u32_e32 v57, vcc, 0, v41, vcc
	v_add_co_u32_e32 v52, vcc, 0xd16000, v40
	s_nop 1
	v_addc_co_u32_e32 v53, vcc, 0, v41, vcc
	v_add_co_u32_e32 v40, vcc, 0xd00000, v40
	s_nop 1
	v_addc_co_u32_e32 v41, vcc, 0, v41, vcc
	v_add_co_u32_e32 v44, vcc, 0xaa16000, v38
	s_nop 1
	v_addc_co_u32_e32 v45, vcc, 0, v39, vcc
	v_add_co_u32_e32 v38, vcc, 0xaa00000, v38
	global_load_dwordx4 v[44:47], v[44:45], off offset:192
	s_nop 0
	global_load_dwordx4 v[48:51], v[40:41], off offset:192
	v_addc_co_u32_e32 v39, vcc, 0, v39, vcc
	global_load_dwordx4 v[38:41], v[38:39], off offset:192
	global_load_dwordx4 v[88:91], v[52:53], off offset:192
	global_load_dwordx4 v[92:95], v[56:57], off offset:192
	global_load_dwordx4 v[96:99], v[60:61], off offset:192
	s_waitcnt vmcnt(4)
	v_mfma_f32_16x16x32_bf16 v[14:17], v[44:47], v[48:51], v[14:17]
	s_nop 0
	s_waitcnt vmcnt(3)
	v_mfma_f32_16x16x32_bf16 v[2:5], v[38:41], v[48:51], v[2:5]
	s_waitcnt vmcnt(2)
	v_mfma_f32_16x16x32_bf16 v[18:21], v[44:47], v[88:91], v[18:21]
	s_waitcnt vmcnt(1)
	v_mfma_f32_16x16x32_bf16 v[6:9], v[44:47], v[92:95], v[6:9]
	v_mfma_f32_16x16x32_bf16 v[30:33], v[38:41], v[88:91], v[30:33]
	v_mfma_f32_16x16x32_bf16 v[26:29], v[38:41], v[92:95], v[26:29]
	s_waitcnt vmcnt(0)
	v_mfma_f32_16x16x32_bf16 v[22:25], v[38:41], v[96:99], v[22:25]
	v_mfma_f32_16x16x32_bf16 v[10:13], v[44:47], v[96:99], v[10:13]

; __device__ __forceinline__ void thin_gemm_ln(const bf16* A, const bf16* Bt, int K, const float* base, float s, const float* g, const float* b, float* outf, bf16* outb, ...
;     ...
;     __syncthreads();
;     const int tm = vcu >> 4, tn = vcu & 15;
;     {   const bf16* ap = A + (size_t)(32 * tm + r) * K + wave * kper + 8 * kq;
;         const bf16* bp = Bt + (size_t)(64 * tn + r) * K + wave * kper + 8 * kq;
;         f32x4m acc[2][4];
; #pragma unroll
;         for (int i = 0; i < 2; ++i)
; #pragma unroll
;             for (int j = 0; j < 4; ++j) acc[i][j] = (f32x4m){0.f, 0.f, 0.f, 0.f};
; #pragma unroll 1
;         for (int s0 = 0; s0 < steps; s0 += 4) {
;             bf16x8 fa[4][2], fb[4][4];
; #pragma unroll
;             for (int q = 0; q < 4; ++q) { const int st = (s0 + q < steps) ? s0 + q : steps - 1;
;                 fa[q][0] = *(const bf16x8*)(ap + 32 * st); fa[q][1] = *(const bf16x8*)(ap + (size_t)16 * K + 32 * st);
; #pragma unroll
;                 for (int j = 0; j < 4; ++j) fb[q][j] = *(const bf16x8*)(bp + (size_t)(16 * j) * K + 32 * st); }
; #pragma unroll
;             for (int q = 0; q < 4; ++q) if (s0 + q < steps) {
; #pragma unroll
;                 for (int j = 0; j < 4; ++j) { acc[0][j] = __builtin_amdgcn_mfma_f32_16x16x32_bf16(fa[q][0], fb[q][j], acc[0][j], 0, 0, 0); acc[1][j] = __builtin_amdgcn_mfma_f32_16x16x32_bf16(fa[q][1], fb[q][j], acc[1][j], 0, 0, 0); } }
;         }
; #pragma unroll
;         for (int i = 0; i < 2; ++i)
; #pragma unroll
;             for (int j = 0; j < 4; ++j)
; #pragma unroll
;                 for (int e = 0; e < 4; ++e) red[(wave * 32 + 16 * i + 4 * kq + e) * 64 + 16 * j + r] = acc[i][j][e]; }
.LBB0_1537:
	v_mov_b32_e32 v70, v0
	s_add_u32 s12, s54, 0x40d90000
	s_addc_u32 s13, s55, 0
	v_readfirstlane_b32 s14, v70
	v_and_b32_e32 v14, 15, v70
	s_ashr_i32 s2, s14, 6
	v_or_b32_e32 v4, s77, v14
	v_ashrrev_i32_e32 v5, 31, v4
	s_lshl_b32 s0, s2, 7
	s_ashr_i32 s1, s0, 31
	v_or_b32_e32 v2, s78, v14
	v_lshlrev_b64 v[4:5], 11, v[4:5]
	v_lshlrev_b32_e32 v2, 11, v2
	v_mov_b32_e32 v3, 0
	s_lshl_b64 s[0:1], s[0:1], 1
	v_lshl_add_u64 v[4:5], s[54:55], 0, v[4:5]
	v_lshl_add_u64 v[8:9], s[84:85], 0, v[2:3]
	v_lshl_add_u64 v[4:5], v[4:5], 0, s[0:1]
	v_and_b32_e32 v2, 48, v70
	v_lshl_add_u64 v[12:13], v[4:5], 0, v[2:3]
	s_mov_b32 s3, 0x26c00000
	v_add_co_u32_e32 v4, vcc, s3, v12
	v_lshl_add_u64 v[8:9], v[8:9], 0, s[0:1]
	s_nop 0
	v_addc_co_u32_e32 v5, vcc, 0, v13, vcc
	s_mov_b32 s0, 0x26c08000
	v_add_co_u32_e32 v62, vcc, s0, v12
	v_lshl_add_u64 v[60:61], v[8:9], 0, v[2:3]
	s_nop 0
	v_addc_co_u32_e32 v63, vcc, 0, v13, vcc
	s_mov_b32 s0, 0x8000
	v_add_co_u32_e32 v64, vcc, s0, v60
	s_mov_b32 s0, 0x10000
	s_nop 0
	v_addc_co_u32_e32 v65, vcc, 0, v61, vcc
	s_barrier
	global_load_dwordx4 v[4:7], v[4:5], off
	v_add_co_u32_e32 v66, vcc, s0, v60
	global_load_dwordx4 v[8:11], v[60:61], off
	global_load_dwordx4 v[16:19], v[62:63], off
	v_addc_co_u32_e32 v67, vcc, 0, v61, vcc
	s_mov_b32 s0, 0x18000
	v_add_co_u32_e32 v68, vcc, s0, v60
	global_load_dwordx4 v[24:27], v[64:65], off
	global_load_dwordx4 v[32:35], v[66:67], off
	v_addc_co_u32_e32 v69, vcc, 0, v61, vcc
	global_load_dwordx4 v[40:43], v[68:69], off
	s_mov_b64 s[0:1], 0x26c00000
	v_lshl_add_u64 v[12:13], v[12:13], 0, s[0:1]
	global_load_dwordx4 v[44:47], v[12:13], off offset:64
	v_lshlrev_b32_e32 v2, 6, v70
	v_and_b32_e32 v2, 0xc00, v2
	v_lshl_or_b32 v2, s2, 13, v2
	v_readlane_b32 s0, v245, 61
	v_readlane_b32 s1, v245, 62
	v_cmp_eq_u32_e32 vcc, 0, v14
	global_load_dwordx4 v[88:91], v[62:63], off offset:64
	global_load_dwordx4 v[92:95], v[68:69], off offset:128
	global_load_dwordx4 v[96:99], v[60:61], off offset:64
	global_load_dwordx4 v[100:103], v[64:65], off offset:64
	global_load_dwordx4 v[104:107], v[66:67], off offset:64
	global_load_dwordx4 v[108:111], v[68:69], off offset:64
	global_load_dwordx4 v[112:115], v[12:13], off offset:128
	global_load_dwordx4 v[116:119], v[62:63], off offset:128
	global_load_dwordx4 v[120:123], v[60:61], off offset:128
	global_load_dwordx4 v[124:127], v[64:65], off offset:128
	global_load_dwordx4 v[128:131], v[66:67], off offset:128
	global_load_dwordx4 v[132:135], v[12:13], off offset:192
	global_load_dwordx4 v[136:139], v[60:61], off offset:192
	global_load_dwordx4 v[140:143], v[62:63], off offset:192
	global_load_dwordx4 v[144:147], v[64:65], off offset:192
	global_load_dwordx4 v[148:151], v[66:67], off offset:192
	global_load_dwordx4 v[152:155], v[68:69], off offset:192
	s_waitcnt vmcnt(17)
	v_mfma_f32_16x16x32_bf16 v[20:23], v[4:7], v[8:11], 0
	v_mfma_f32_16x16x32_bf16 v[8:11], v[16:19], v[8:11], 0
	v_mfma_f32_16x16x32_bf16 v[28:31], v[4:7], v[24:27], 0
	v_mfma_f32_16x16x32_bf16 v[24:27], v[16:19], v[24:27], 0
	v_mfma_f32_16x16x32_bf16 v[36:39], v[4:7], v[32:35], 0
	v_mfma_f32_16x16x32_bf16 v[32:35], v[16:19], v[32:35], 0
	v_mfma_f32_16x16x32_bf16 v[4:7], v[4:7], v[40:43], 0
	v_mfma_f32_16x16x32_bf16 v[16:19], v[16:19], v[40:43], 0
	s_waitcnt vmcnt(14)
	v_mfma_f32_16x16x32_bf16 v[20:23], v[44:47], v[96:99], v[20:23]
	v_mfma_f32_16x16x32_bf16 v[8:11], v[88:91], v[96:99], v[8:11]
	s_waitcnt vmcnt(13)
	v_mfma_f32_16x16x32_bf16 v[28:31], v[44:47], v[100:103], v[28:31]
	v_mfma_f32_16x16x32_bf16 v[24:27], v[88:91], v[100:103], v[24:27]
	s_waitcnt vmcnt(12)
	v_mfma_f32_16x16x32_bf16 v[36:39], v[44:47], v[104:107], v[36:39]
	v_mfma_f32_16x16x32_bf16 v[32:35], v[88:91], v[104:107], v[32:35]
	s_waitcnt vmcnt(11)
	v_mfma_f32_16x16x32_bf16 v[4:7], v[44:47], v[108:111], v[4:7]
	v_mfma_f32_16x16x32_bf16 v[16:19], v[88:91], v[108:111], v[16:19]
	s_waitcnt vmcnt(8)
	v_mfma_f32_16x16x32_bf16 v[20:23], v[112:115], v[120:123], v[20:23]
	v_mfma_f32_16x16x32_bf16 v[8:11], v[116:119], v[120:123], v[8:11]
	v_mfma_f32_16x16x32_bf16 v[4:7], v[112:115], v[92:95], v[4:7]
	s_waitcnt vmcnt(7)
	v_mfma_f32_16x16x32_bf16 v[28:31], v[112:115], v[124:127], v[28:31]
	v_mfma_f32_16x16x32_bf16 v[24:27], v[116:119], v[124:127], v[24:27]
	s_waitcnt vmcnt(6)
	v_mfma_f32_16x16x32_bf16 v[36:39], v[112:115], v[128:131], v[36:39]
	v_mfma_f32_16x16x32_bf16 v[32:35], v[116:119], v[128:131], v[32:35]
	v_lshlrev_b32_e32 v12, 2, v14
	v_mfma_f32_16x16x32_bf16 v[16:19], v[116:119], v[92:95], v[16:19]
	v_add3_u32 v2, 0, v12, v2
	s_waitcnt vmcnt(4)
	v_mfma_f32_16x16x32_bf16 v[20:23], v[132:135], v[136:139], v[20:23]
	v_or_b32_e32 v15, s78, v12
	v_and_b32_e32 v12, 63, v70
	s_waitcnt vmcnt(3)
	v_mfma_f32_16x16x32_bf16 v[8:11], v[140:143], v[136:139], v[8:11]
	s_waitcnt vmcnt(2)
	v_mfma_f32_16x16x32_bf16 v[28:31], v[132:135], v[144:147], v[28:31]
	s_nop 7
	ds_write2_b32 v2, v20, v28 offset1:16
	ds_write2_b32 v2, v21, v29 offset0:64 offset1:80
	ds_write2_b32 v2, v22, v30 offset0:128 offset1:144
	s_waitcnt vmcnt(1)
	v_mfma_f32_16x16x32_bf16 v[36:39], v[132:135], v[148:151], v[36:39]
	s_waitcnt vmcnt(0)
	v_mfma_f32_16x16x32_bf16 v[4:7], v[132:135], v[152:155], v[4:7]
	ds_write2_b32 v2, v23, v31 offset0:192 offset1:208
	s_nop 6
	ds_write2_b32 v2, v36, v4 offset0:32 offset1:48
	ds_write2_b32 v2, v37, v5 offset0:96 offset1:112
	v_mfma_f32_16x16x32_bf16 v[20:23], v[140:143], v[144:147], v[24:27]
	ds_write2_b32 v2, v38, v6 offset0:160 offset1:176
	ds_write2_b32 v2, v39, v7 offset0:224 offset1:240
	v_add_u32_e32 v2, 0x1000, v2
	s_nop 4
	ds_write2_b32 v2, v8, v20 offset1:16
	ds_write2_b32 v2, v9, v21 offset0:64 offset1:80
	ds_write2_b32 v2, v10, v22 offset0:128 offset1:144
	v_mfma_f32_16x16x32_bf16 v[4:7], v[140:143], v[148:151], v[32:35]
	v_ashrrev_i32_e32 v10, 4, v70
	v_add_u32_e32 v8, s77, v10
	v_ashrrev_i32_e32 v9, 31, v8
	v_mfma_f32_16x16x32_bf16 v[16:19], v[140:143], v[152:155], v[16:19]
	ds_write2_b32 v2, v11, v23 offset0:192 offset1:208
	s_nop 6
	ds_write2_b32 v2, v4, v16 offset0:32 offset1:48
	ds_write2_b32 v2, v5, v17 offset0:96 offset1:112
	ds_write2_b32 v2, v6, v18 offset0:160 offset1:176
	ds_write2_b32 v2, v7, v19 offset0:224 offset1:240
	v_lshlrev_b64 v[4:5], 12, v[8:9]
	v_lshl_add_u64 v[4:5], s[0:1], 0, v[4:5]
	v_lshlrev_b32_e32 v2, 2, v15
	v_lshl_add_u64 v[4:5], v[4:5], 0, v[2:3]
	s_waitcnt lgkmcnt(0)
	s_barrier
; #define LAS __attribute__((address_space(3)))
; #define SDPP(x, ctrl) __builtin_bit_cast(float, __builtin_amdgcn_update_dpp(0, __builtin_bit_cast(int, (x)), (ctrl), 0xF, 0xF, false))
; __device__ __forceinline__ void thin_gemm_ln(const bf16* A, const bf16* Bt, int K, const float* base, float s, const float* g, const float* b, float* outf, bf16* outb, ...
;     ...
;     const int row = tid >> 4, cg = tid & 15, grow = 32 * tm + row, gcol = 64 * tn + 4 * cg;
;     f32x4m v = (f32x4m){0.f, 0.f, 0.f, 0.f};
; #pragma unroll
;     for (int w = 0; w < 8; ++w) v += *(const LAS f32x4m*)(red + (w * 32 + row) * 64 + 4 * cg);
;     v = v * s + *(const f32x4m*)(base + (size_t)grow * DM + gcol) * ALPHA;
;     float s1 = (v.x + v.y) + (v.z + v.w);
;     s1 += SDPP(s1, 0xB1); s1 += SDPP(s1, 0x4E); s1 += SDPP(s1, 0x141); s1 += SDPP(s1, 0x140);
;     const float mt = s1 * (1.f / 64.f); const f32x4m d = v - mt;
;     float q = (d.x * d.x + d.y * d.y) + (d.z * d.z + d.w * d.w);
;     q += SDPP(q, 0xB1); q += SDPP(q, 0x4E); q += SDPP(q, 0x141); q += SDPP(q, 0x140);
;     if (cg == 0) __hip_atomic_store(slots + (size_t)grow * 16 + tn, ((unsigned long long)__float_as_uint(q) << 32) | __float_as_uint(mt), __ATOMIC_RELAXED, __HIP_MEMORY_SCOPE_AGENT);
	global_load_dwordx4 v[4:7], v[4:5], off
	v_lshlrev_b32_e32 v10, 8, v10
	v_lshlrev_b32_e32 v11, 4, v14
	v_add3_u32 v10, 0, v10, v11
	ds_read_b128 v[16:19], v10
	ds_read_b128 v[20:23], v10 offset:8192
	ds_read_b128 v[24:27], v10 offset:16384
	ds_read_b128 v[28:31], v10 offset:24576
	ds_read_b128 v[32:35], v10 offset:32768
	ds_read_b128 v[36:39], v10 offset:40960
	ds_read_b128 v[40:43], v10 offset:49152
	ds_read_b128 v[44:47], v10 offset:57344
	s_waitcnt lgkmcnt(7)
	v_pk_add_f32 v[10:11], v[18:19], 0 op_sel_hi:[1,0]
	v_pk_add_f32 v[16:17], v[16:17], 0 op_sel_hi:[1,0]
	s_waitcnt lgkmcnt(6)
	v_pk_add_f32 v[10:11], v[10:11], v[22:23]
	v_pk_add_f32 v[16:17], v[16:17], v[20:21]
	s_waitcnt lgkmcnt(5)
	v_pk_add_f32 v[10:11], v[10:11], v[26:27]
	v_pk_add_f32 v[16:17], v[16:17], v[24:25]
	s_waitcnt lgkmcnt(4)
	v_pk_add_f32 v[10:11], v[10:11], v[30:31]
	v_pk_add_f32 v[16:17], v[16:17], v[28:29]
	s_waitcnt lgkmcnt(3)
	v_pk_add_f32 v[10:11], v[10:11], v[34:35]
	v_pk_add_f32 v[16:17], v[16:17], v[32:33]
	s_waitcnt lgkmcnt(2)
	v_pk_add_f32 v[10:11], v[10:11], v[38:39]
	v_pk_add_f32 v[16:17], v[16:17], v[36:37]
	s_waitcnt lgkmcnt(1)
	v_pk_add_f32 v[10:11], v[10:11], v[42:43]
	v_pk_add_f32 v[16:17], v[16:17], v[40:41]
	s_mov_b32 s1, 0
	s_mov_b32 s0, 0x3f9837f0
	s_waitcnt lgkmcnt(0)
	v_pk_add_f32 v[10:11], v[10:11], v[46:47]
	v_pk_add_f32 v[16:17], v[16:17], v[44:45]
	s_waitcnt vmcnt(0)
	v_pk_fma_f32 v[6:7], v[6:7], s[0:1], v[10:11] op_sel_hi:[1,0,1]
	v_pk_fma_f32 v[4:5], v[4:5], s[0:1], v[16:17] op_sel_hi:[1,0,1]
	v_mov_b32_e32 v17, v7
	v_pk_mov_b32 v[10:11], v[4:5], v[6:7] op_sel:[1,0]
	v_mov_b32_e32 v16, v4
	v_pk_add_f32 v[10:11], v[10:11], v[16:17]
	s_nop 0
	v_add_f32_e32 v10, v10, v11
	s_nop 1
	v_add_f32_dpp v10, v10, v10 quad_perm:[1,0,3,2] row_mask:0xf bank_mask:0xf bound_ctrl:1
	s_nop 1
	v_add_f32_dpp v10, v10, v10 quad_perm:[2,3,0,1] row_mask:0xf bank_mask:0xf bound_ctrl:1
	s_nop 1
	v_add_f32_dpp v10, v10, v10 row_half_mirror row_mask:0xf bank_mask:0xf bound_ctrl:1
	s_nop 1
	v_add_f32_dpp v13, v10, v10 row_mirror row_mask:0xf bank_mask:0xf bound_ctrl:1
	v_fmamk_f32 v11, v13, 0xbc800000, v7
	v_fmamk_f32 v17, v13, 0xbc800000, v5
	v_fmamk_f32 v10, v13, 0xbc800000, v6
	v_fmamk_f32 v16, v13, 0xbc800000, v4
	v_mul_f32_e32 v17, v17, v17
	v_mul_f32_e32 v11, v11, v11
	v_fmac_f32_e32 v17, v16, v16
	v_fmac_f32_e32 v11, v10, v10
	v_add_f32_e32 v10, v17, v11
	s_nop 1
	v_add_f32_dpp v10, v10, v10 quad_perm:[1,0,3,2] row_mask:0xf bank_mask:0xf bound_ctrl:1
	s_nop 1
	v_add_f32_dpp v10, v10, v10 quad_perm:[2,3,0,1] row_mask:0xf bank_mask:0xf bound_ctrl:1
	s_nop 1
	v_add_f32_dpp v16, v10, v10 row_half_mirror row_mask:0xf bank_mask:0xf bound_ctrl:1
	v_lshlrev_b64 v[10:11], 7, v[8:9]
	s_nop 0
	v_mov_b32_dpp v3, v16 row_mirror row_mask:0xf bank_mask:0xf
	s_and_saveexec_b64 s[2:3], vcc
	s_cbranch_execz .LBB0_1539
	v_add_f32_e32 v19, v16, v3
	v_lshl_add_u64 v[16:17], s[12:13], 0, v[10:11]
	s_lshl_b32 s0, s76, 3
	v_mul_f32_e32 v18, 0x3c800000, v13
	v_lshl_add_u64 v[16:17], v[16:17], 0, s[0:1]
	global_store_dwordx2 v[16:17], v[18:19], off sc1

; __device__ __forceinline__ void thin_gemm_ln(const bf16* A, const bf16* Bt, int K, const float* base, float s, const float* g, const float* b, float* outf, bf16* outb, ...
;     ...
;         for (int s0 = 0; s0 < steps; s0 += 4) {
;             bf16x8 fa[4][2], fb[4][4];
; #pragma unroll
;             for (int q = 0; q < 4; ++q) { const int st = (s0 + q < steps) ? s0 + q : steps - 1;
;                 fa[q][0] = *(const bf16x8*)(ap + 32 * st); fa[q][1] = *(const bf16x8*)(ap + (size_t)16 * K + 32 * st);
; #pragma unroll
;                 for (int j = 0; j < 4; ++j) fb[q][j] = *(const bf16x8*)(bp + (size_t)(16 * j) * K + 32 * st); }
; #pragma unroll
;             for (int q = 0; q < 4; ++q) if (s0 + q < steps) {
; #pragma unroll
;                 for (int j = 0; j < 4; ++j) { acc[0][j] = __builtin_amdgcn_mfma_f32_16x16x32_bf16(fa[q][0], fb[q][j], acc[0][j], 0, 0, 0); acc[1][j] = __builtin_amdgcn_mfma_f32_16x16x32_bf16(fa[q][1], fb[q][j], acc[1][j], 0, 0, 0); } }
;         }
.LBB0_1756:
	v_lshl_add_u64 v[38:39], s[54:55], 0, v[34:35]
	v_add_co_u32_e32 v76, vcc, 0xaa00000, v38
	v_lshl_add_u64 v[40:41], s[54:55], 0, v[36:37]
	s_nop 0
	v_addc_co_u32_e32 v77, vcc, 0, v39, vcc
	v_add_co_u32_e32 v78, vcc, 0xaa16000, v38
	s_mov_b64 s[0:1], vcc
	v_add_co_u32_e32 v80, vcc, 0x2900000, v40
	global_load_dwordx4 v[44:47], v[76:77], off
	s_nop 0
	v_addc_co_u32_e32 v81, vcc, 0, v41, vcc
	v_add_co_u32_e32 v82, vcc, 0x2916000, v40
	global_load_dwordx4 v[48:51], v[80:81], off
	global_load_dwordx4 v[52:55], v[76:77], off offset:64
	v_addc_co_u32_e32 v83, vcc, 0, v41, vcc
	v_add_co_u32_e32 v84, vcc, 0x292c000, v40
	global_load_dwordx4 v[56:59], v[80:81], off offset:64
	global_load_dwordx4 v[60:63], v[82:83], off
	v_addc_co_u32_e32 v85, vcc, 0, v41, vcc
	v_addc_co_u32_e64 v79, vcc, 0, v39, s[0:1]
	global_load_dwordx4 v[64:67], v[84:85], off
	global_load_dwordx4 v[72:75], v[78:79], off
	v_add_co_u32_e32 v86, vcc, 0x2942000, v40
	global_load_dwordx4 v[68:71], v[84:85], off offset:64
	s_nop 0
	v_addc_co_u32_e32 v87, vcc, 0, v41, vcc
	s_cmp_gt_u32 s5, 10
	global_load_dwordx4 v[88:91], v[86:87], off
	global_load_dwordx4 v[92:95], v[78:79], off offset:128
	global_load_dwordx4 v[96:99], v[82:83], off offset:64
	global_load_dwordx4 v[100:103], v[78:79], off offset:64
	global_load_dwordx4 v[104:107], v[86:87], off offset:64
	global_load_dwordx4 v[108:111], v[84:85], off offset:128
	global_load_dwordx4 v[112:115], v[76:77], off offset:128
	global_load_dwordx4 v[116:119], v[80:81], off offset:128
	global_load_dwordx4 v[120:123], v[82:83], off offset:128
	global_load_dwordx4 v[124:127], v[86:87], off offset:128
	s_waitcnt vmcnt(16)
	v_mfma_f32_16x16x32_bf16 v[2:5], v[44:47], v[48:51], v[2:5]
	s_waitcnt vmcnt(11)
	v_mfma_f32_16x16x32_bf16 v[14:17], v[72:75], v[48:51], v[14:17]
	v_mfma_f32_16x16x32_bf16 v[30:33], v[44:47], v[60:63], v[30:33]
	v_mfma_f32_16x16x32_bf16 v[26:29], v[44:47], v[64:67], v[26:29]
	v_mfma_f32_16x16x32_bf16 v[18:21], v[72:75], v[60:63], v[18:21]
	s_waitcnt vmcnt(9)
	v_mfma_f32_16x16x32_bf16 v[22:25], v[44:47], v[88:91], v[22:25]
	v_mfma_f32_16x16x32_bf16 v[10:13], v[72:75], v[88:91], v[10:13]
	s_waitcnt vmcnt(7)
	v_mfma_f32_16x16x32_bf16 v[30:33], v[52:55], v[96:99], v[30:33]
	s_waitcnt vmcnt(6)
	v_mfma_f32_16x16x32_bf16 v[18:21], v[100:103], v[96:99], v[18:21]
	v_mfma_f32_16x16x32_bf16 v[2:5], v[52:55], v[56:59], v[2:5]
	v_mfma_f32_16x16x32_bf16 v[14:17], v[100:103], v[56:59], v[14:17]
	v_mfma_f32_16x16x32_bf16 v[26:29], v[52:55], v[68:71], v[26:29]
	s_waitcnt vmcnt(5)
	v_mfma_f32_16x16x32_bf16 v[22:25], v[52:55], v[104:107], v[22:25]
	v_mfma_f32_16x16x32_bf16 v[10:13], v[100:103], v[104:107], v[10:13]
	v_mfma_f32_16x16x32_bf16 v[6:9], v[72:75], v[64:67], v[6:9]
	v_mfma_f32_16x16x32_bf16 v[6:9], v[100:103], v[68:71], v[6:9]
	s_waitcnt vmcnt(2)
	v_mfma_f32_16x16x32_bf16 v[2:5], v[112:115], v[116:119], v[2:5]
	v_mfma_f32_16x16x32_bf16 v[14:17], v[92:95], v[116:119], v[14:17]
	s_waitcnt vmcnt(1)
	v_mfma_f32_16x16x32_bf16 v[30:33], v[112:115], v[120:123], v[30:33]
	v_mfma_f32_16x16x32_bf16 v[26:29], v[112:115], v[108:111], v[26:29]
	v_mfma_f32_16x16x32_bf16 v[18:21], v[92:95], v[120:123], v[18:21]
	v_mfma_f32_16x16x32_bf16 v[6:9], v[92:95], v[108:111], v[6:9]
	s_waitcnt vmcnt(0)
	v_mfma_f32_16x16x32_bf16 v[22:25], v[112:115], v[124:127], v[22:25]
	v_mfma_f32_16x16x32_bf16 v[10:13], v[92:95], v[124:127], v[10:13]
	s_cbranch_scc1 .LBB0_1758
	v_add_co_u32_e32 v60, vcc, 0x2942000, v40
	s_nop 1
	v_addc_co_u32_e32 v61, vcc, 0, v41, vcc
	v_add_co_u32_e32 v56, vcc, 0x292c000, v40
	s_nop 1
	v_addc_co_u32_e32 v57, vcc, 0, v41, vcc
	v_add_co_u32_e32 v52, vcc, 0x2916000, v40
	s_nop 1
	v_addc_co_u32_e32 v53, vcc, 0, v41, vcc
	v_add_co_u32_e32 v40, vcc, 0x2900000, v40
	s_nop 1
	v_addc_co_u32_e32 v41, vcc, 0, v41, vcc
	v_add_co_u32_e32 v54, vcc, 0xaa16000, v38
	s_nop 1
	v_addc_co_u32_e32 v55, vcc, 0, v39, vcc
	v_add_co_u32_e32 v38, vcc, 0xaa00000, v38
	global_load_dwordx4 v[44:47], v[54:55], off offset:192
	global_load_dwordx4 v[48:51], v[40:41], off offset:192
	v_addc_co_u32_e32 v39, vcc, 0, v39, vcc
	global_load_dwordx4 v[38:41], v[38:39], off offset:192
	global_load_dwordx4 v[88:91], v[52:53], off offset:192
	global_load_dwordx4 v[92:95], v[56:57], off offset:192
	global_load_dwordx4 v[96:99], v[60:61], off offset:192
	s_waitcnt vmcnt(4)
	v_mfma_f32_16x16x32_bf16 v[14:17], v[44:47], v[48:51], v[14:17]
	s_nop 0
	s_waitcnt vmcnt(3)
	v_mfma_f32_16x16x32_bf16 v[2:5], v[38:41], v[48:51], v[2:5]
	s_waitcnt vmcnt(2)
	v_mfma_f32_16x16x32_bf16 v[18:21], v[44:47], v[88:91], v[18:21]
	s_waitcnt vmcnt(1)
	v_mfma_f32_16x16x32_bf16 v[6:9], v[44:47], v[92:95], v[6:9]
	v_mfma_f32_16x16x32_bf16 v[30:33], v[38:41], v[88:91], v[30:33]
	v_mfma_f32_16x16x32_bf16 v[26:29], v[38:41], v[92:95], v[26:29]
	s_waitcnt vmcnt(0)
	v_mfma_f32_16x16x32_bf16 v[22:25], v[38:41], v[96:99], v[22:25]
	v_mfma_f32_16x16x32_bf16 v[10:13], v[44:47], v[96:99], v[10:13]
